# attention loop end: the two v_pk_fma_f32 of the row-sum update split into four v_fma_f32 (packed fp32 between MFMAs stalls issue)
# speedup vs baseline: 1.0026x; 1.0026x over previous
.LBB0_977:
	s_add_u32 s30, s30, 0x100000
	s_addc_u32 s31, s31, 0
	v_fma_f32 v160, v200, v204, v206
	v_fma_f32 v161, v201, v205, v207
	s_add_u32 s10, s10, 0x4000
	v_fma_f32 v200, v160, v208, v194
	v_fma_f32 v201, v161, v209, v195
	s_addc_u32 s11, s11, 0
	s_add_i32 s4, s4, 2
	s_and_b64 vcc, exec, s[34:35]
	s_cbranch_vccnz .LBB0_979
	s_mov_b32 s25, s8
	s_mov_b32 s8, s19
	v_mov_b32_e32 v204, v192
	v_mov_b32_e32 v205, v193
	s_branch .LBB0_961
